# gdn_prep k_tail^T: threads re-mapped to (row, token octet) so each store instruction writes 8 full 128-B rows; per-token decay exp computed once per thread
# speedup vs baseline: 1.0280x; 1.0073x over previous
.LBB0_357:
	s_or_b64 exec, exec, s[44:45]
	v_cvt_pk_bf16_f32 v0, v0, v0
	global_store_short v[62:63], v0, off offset:224
	ds_read2st64_b32 v[0:1], v175 offset1:2
	s_add_u32 s44, s74, s28
	s_addc_u32 s45, s75, s29
	v_lshl_add_u64 v[16:17], s[44:45], 0, v[58:59]
	s_waitcnt lgkmcnt(0)
	v_mul_f32_e32 v0, 0x3fb8aa3b, v0
	v_exp_f32_e32 v0, v0
	s_nop 0
	v_mul_f32_e32 v18, v1, v0
	v_and_b32_e32 v110, 3, v160
	v_mul_u32_u24_e32 v110, 48, v110
	v_sub_u32_e32 v111, v184, v110
	v_sub_u32_e32 v114, 0, v110
	v_ashrrev_i32_e32 v115, 31, v114
	v_lshl_add_u64 v[112:113], v[16:17], 0, v[114:115]
	ds_read_b128 v[0:3], v111
	ds_read_b128 v[4:7], v111 offset:64
	ds_read_b128 v[8:11], v111 offset:128
	ds_read_b128 v[12:15], v111 offset:192
	s_waitcnt lgkmcnt(0)
	v_lshlrev_b32_e32 v19, 16, v0
	v_and_b32_e32 v0, 0xffff0000, v0
	v_lshlrev_b32_e32 v20, 16, v1
	v_and_b32_e32 v1, 0xffff0000, v1
	v_lshlrev_b32_e32 v22, 16, v3
	v_and_b32_e32 v3, 0xffff0000, v3
	v_lshlrev_b32_e32 v21, 16, v2
	v_and_b32_e32 v2, 0xffff0000, v2
	v_mul_f32_e32 v0, v18, v0
	v_mul_f32_e32 v1, v18, v1
	v_mul_f32_e32 v3, v18, v3
	v_mul_f32_e32 v19, v18, v19
	v_mul_f32_e32 v20, v18, v20
	v_mul_f32_e32 v2, v18, v2
	v_mul_f32_e32 v22, v18, v22
	v_cvt_pk_bf16_f32 v0, v19, v0
	v_cvt_pk_bf16_f32 v1, v20, v1
	v_cvt_pk_bf16_f32 v3, v22, v3
	v_mul_f32_e32 v21, v18, v21
	v_cvt_pk_bf16_f32 v2, v21, v2
	global_store_dwordx4 v[112:113], v[0:3], off offset:-32
	s_waitcnt lgkmcnt(2)
	s_nop 0
	v_lshlrev_b32_e32 v0, 16, v4
	v_and_b32_e32 v1, 0xffff0000, v4
	v_and_b32_e32 v3, 0xffff0000, v5
	v_lshlrev_b32_e32 v2, 16, v5
	v_lshlrev_b32_e32 v4, 16, v6
	v_and_b32_e32 v5, 0xffff0000, v6
	v_lshlrev_b32_e32 v6, 16, v7
	v_and_b32_e32 v7, 0xffff0000, v7
	v_mul_f32_e32 v0, v18, v0
	v_mul_f32_e32 v1, v18, v1
	v_mul_f32_e32 v3, v18, v3
	v_mul_f32_e32 v2, v18, v2
	v_mul_f32_e32 v6, v18, v6
	v_mul_f32_e32 v7, v18, v7
	v_cvt_pk_bf16_f32 v0, v0, v1
	v_cvt_pk_bf16_f32 v1, v2, v3
	v_cvt_pk_bf16_f32 v3, v6, v7
	v_mul_f32_e32 v4, v18, v4
	v_mul_f32_e32 v5, v18, v5
	v_cvt_pk_bf16_f32 v2, v4, v5
	global_store_dwordx4 v[112:113], v[0:3], off offset:32
	s_waitcnt lgkmcnt(1)
	v_lshlrev_b32_e32 v6, 16, v11
	v_and_b32_e32 v7, 0xffff0000, v11
	v_lshlrev_b32_e32 v0, 16, v8
	v_and_b32_e32 v1, 0xffff0000, v8
	v_and_b32_e32 v3, 0xffff0000, v9
	v_lshlrev_b32_e32 v2, 16, v9
	v_mul_f32_e32 v0, v18, v0
	v_mul_f32_e32 v1, v18, v1
	v_mul_f32_e32 v3, v18, v3
	v_lshlrev_b32_e32 v4, 16, v10
	v_and_b32_e32 v5, 0xffff0000, v10
	v_mul_f32_e32 v2, v18, v2
	v_mul_f32_e32 v6, v18, v6
	v_mul_f32_e32 v7, v18, v7
	v_cvt_pk_bf16_f32 v0, v0, v1
	v_cvt_pk_bf16_f32 v1, v2, v3
	v_cvt_pk_bf16_f32 v3, v6, v7
	v_mul_f32_e32 v4, v18, v4
	v_mul_f32_e32 v5, v18, v5
	v_cvt_pk_bf16_f32 v2, v4, v5
	global_store_dwordx4 v[112:113], v[0:3], off offset:96
	s_waitcnt lgkmcnt(0)
	v_lshlrev_b32_e32 v6, 16, v15
	v_and_b32_e32 v7, 0xffff0000, v15
	v_lshlrev_b32_e32 v0, 16, v12
	v_and_b32_e32 v1, 0xffff0000, v12
	v_and_b32_e32 v3, 0xffff0000, v13
	v_lshlrev_b32_e32 v2, 16, v13
	v_mul_f32_e32 v0, v18, v0
	v_mul_f32_e32 v1, v18, v1
	v_mul_f32_e32 v3, v18, v3
	v_lshlrev_b32_e32 v4, 16, v14
	v_and_b32_e32 v5, 0xffff0000, v14
	v_mul_f32_e32 v2, v18, v2
	v_mul_f32_e32 v6, v18, v6
	v_mul_f32_e32 v7, v18, v7
	v_cvt_pk_bf16_f32 v0, v0, v1
	v_cvt_pk_bf16_f32 v1, v2, v3
	v_cvt_pk_bf16_f32 v3, v6, v7
	v_mul_f32_e32 v4, v18, v4
	v_mul_f32_e32 v5, v18, v5
	v_cvt_pk_bf16_f32 v2, v4, v5
	global_store_dwordx4 v[112:113], v[0:3], off offset:160
	v_and_b32_e32 v110, 63, v160
	v_and_b32_e32 v111, 7, v110
	v_lshrrev_b32_e32 v112, 3, v110
	v_lshl_add_u32 v113, v111, 5, v168
	ds_read_b32 v2, v168 offset:252
	ds_read_b128 v[124:127], v113
	ds_read_b128 v[128:131], v113 offset:16
	ds_read_b128 v[116:119], v113 offset:768
	ds_read_b128 v[120:123], v113 offset:784
	v_bfe_u32 v114, v160, 6, 2
	v_lshl_add_u32 v114, v114, 5, v112
	v_lshlrev_b32_e32 v114, 1, v114
	v_mul_u32_u24_e32 v115, 0x880, v111
	v_add3_u32 v114, v114, v115, v168
	v_add_u32_e32 v114, 0xffff5000, v114
	v_lshlrev_b32_e32 v132, 7, v112
	v_lshl_add_u32 v132, v111, 4, v132
	v_lshrrev_b32_e32 v115, 1, v110
	v_lshlrev_b32_e32 v115, 7, v115
	v_sub_u32_e32 v132, v132, v115
	v_and_b32_e32 v115, 1, v110
	v_lshlrev_b32_e32 v115, 6, v115
	v_sub_u32_e32 v132, v132, v115
	v_lshl_add_u64 v[0:1], s[44:45], 0, v[60:61]
	v_ashrrev_i32_e32 v133, 31, v132
	s_nop 0
	v_lshl_add_u64 v[134:135], v[0:1], 0, v[132:133]
	ds_read_u16 v3, v114 offset:0
	ds_read_u16 v4, v114 offset:272
	ds_read_u16 v5, v114 offset:544
	ds_read_u16 v6, v114 offset:816
	ds_read_u16 v7, v114 offset:1088
	ds_read_u16 v8, v114 offset:1360
	ds_read_u16 v9, v114 offset:1632
	ds_read_u16 v10, v114 offset:1904
	s_waitcnt lgkmcnt(0)
	v_sub_f32_e32 v124, v2, v124
	v_mul_f32_e32 v124, 0x3fb8aa3b, v124
	v_exp_f32_e32 v124, v124
	v_sub_f32_e32 v125, v2, v125
	v_mul_f32_e32 v125, 0x3fb8aa3b, v125
	v_exp_f32_e32 v125, v125
	v_sub_f32_e32 v126, v2, v126
	v_mul_f32_e32 v126, 0x3fb8aa3b, v126
	v_exp_f32_e32 v126, v126
	v_sub_f32_e32 v127, v2, v127
	v_mul_f32_e32 v127, 0x3fb8aa3b, v127
	v_exp_f32_e32 v127, v127
	v_sub_f32_e32 v128, v2, v128
	v_mul_f32_e32 v128, 0x3fb8aa3b, v128
	v_exp_f32_e32 v128, v128
	v_sub_f32_e32 v129, v2, v129
	v_mul_f32_e32 v129, 0x3fb8aa3b, v129
	v_exp_f32_e32 v129, v129
	v_sub_f32_e32 v130, v2, v130
	v_mul_f32_e32 v130, 0x3fb8aa3b, v130
	v_exp_f32_e32 v130, v130
	v_sub_f32_e32 v131, v2, v131
	v_mul_f32_e32 v131, 0x3fb8aa3b, v131
	v_exp_f32_e32 v131, v131
	s_nop 0
	v_lshlrev_b32_e32 v3, 16, v3
	v_mul_f32_e32 v3, v116, v3
	v_mul_f32_e32 v3, v3, v124
	v_lshlrev_b32_e32 v4, 16, v4
	v_mul_f32_e32 v4, v117, v4
	v_mul_f32_e32 v4, v4, v125
	v_lshlrev_b32_e32 v5, 16, v5
	v_mul_f32_e32 v5, v118, v5
	v_mul_f32_e32 v5, v5, v126
	v_lshlrev_b32_e32 v6, 16, v6
	v_mul_f32_e32 v6, v119, v6
	v_mul_f32_e32 v6, v6, v127
	v_lshlrev_b32_e32 v7, 16, v7
	v_mul_f32_e32 v7, v120, v7
	v_mul_f32_e32 v7, v7, v128
	v_lshlrev_b32_e32 v8, 16, v8
	v_mul_f32_e32 v8, v121, v8
	v_mul_f32_e32 v8, v8, v129
	v_lshlrev_b32_e32 v9, 16, v9
	v_mul_f32_e32 v9, v122, v9
	v_mul_f32_e32 v9, v9, v130
	v_lshlrev_b32_e32 v10, 16, v10
	v_mul_f32_e32 v10, v123, v10
	v_mul_f32_e32 v10, v10, v131
	v_cvt_pk_bf16_f32 v12, v3, v4
	v_cvt_pk_bf16_f32 v13, v5, v6
	v_cvt_pk_bf16_f32 v14, v7, v8
	v_cvt_pk_bf16_f32 v15, v9, v10
	global_store_dwordx4 v[134:135], v[12:15], off offset:-32
	ds_read_u16 v3, v114 offset:16
	ds_read_u16 v4, v114 offset:288
	ds_read_u16 v5, v114 offset:560
	ds_read_u16 v6, v114 offset:832
	ds_read_u16 v7, v114 offset:1104
	ds_read_u16 v8, v114 offset:1376
	ds_read_u16 v9, v114 offset:1648
	ds_read_u16 v10, v114 offset:1920
	s_waitcnt lgkmcnt(0)
	v_lshlrev_b32_e32 v3, 16, v3
	v_mul_f32_e32 v3, v116, v3
	v_mul_f32_e32 v3, v3, v124
	v_lshlrev_b32_e32 v4, 16, v4
	v_mul_f32_e32 v4, v117, v4
	v_mul_f32_e32 v4, v4, v125
	v_lshlrev_b32_e32 v5, 16, v5
	v_mul_f32_e32 v5, v118, v5
	v_mul_f32_e32 v5, v5, v126
	v_lshlrev_b32_e32 v6, 16, v6
	v_mul_f32_e32 v6, v119, v6
	v_mul_f32_e32 v6, v6, v127
	v_lshlrev_b32_e32 v7, 16, v7
	v_mul_f32_e32 v7, v120, v7
	v_mul_f32_e32 v7, v7, v128
	v_lshlrev_b32_e32 v8, 16, v8
	v_mul_f32_e32 v8, v121, v8
	v_mul_f32_e32 v8, v8, v129
	v_lshlrev_b32_e32 v9, 16, v9
	v_mul_f32_e32 v9, v122, v9
	v_mul_f32_e32 v9, v9, v130
	v_lshlrev_b32_e32 v10, 16, v10
	v_mul_f32_e32 v10, v123, v10
	v_mul_f32_e32 v10, v10, v131
	v_cvt_pk_bf16_f32 v12, v3, v4
	v_cvt_pk_bf16_f32 v13, v5, v6
	v_cvt_pk_bf16_f32 v14, v7, v8
	v_cvt_pk_bf16_f32 v15, v9, v10
	global_store_dwordx4 v[134:135], v[12:15], off offset:992
	ds_read_u16 v3, v114 offset:32
	ds_read_u16 v4, v114 offset:304
	ds_read_u16 v5, v114 offset:576
	ds_read_u16 v6, v114 offset:848
	ds_read_u16 v7, v114 offset:1120
	ds_read_u16 v8, v114 offset:1392
	ds_read_u16 v9, v114 offset:1664
	ds_read_u16 v10, v114 offset:1936
	s_waitcnt lgkmcnt(0)
	v_lshlrev_b32_e32 v3, 16, v3
	v_mul_f32_e32 v3, v116, v3
	v_mul_f32_e32 v3, v3, v124
	v_lshlrev_b32_e32 v4, 16, v4
	v_mul_f32_e32 v4, v117, v4
	v_mul_f32_e32 v4, v4, v125
	v_lshlrev_b32_e32 v5, 16, v5
	v_mul_f32_e32 v5, v118, v5
	v_mul_f32_e32 v5, v5, v126
	v_lshlrev_b32_e32 v6, 16, v6
	v_mul_f32_e32 v6, v119, v6
	v_mul_f32_e32 v6, v6, v127
	v_lshlrev_b32_e32 v7, 16, v7
	v_mul_f32_e32 v7, v120, v7
	v_mul_f32_e32 v7, v7, v128
	v_lshlrev_b32_e32 v8, 16, v8
	v_mul_f32_e32 v8, v121, v8
	v_mul_f32_e32 v8, v8, v129
	v_lshlrev_b32_e32 v9, 16, v9
	v_mul_f32_e32 v9, v122, v9
	v_mul_f32_e32 v9, v9, v130
	v_lshlrev_b32_e32 v10, 16, v10
	v_mul_f32_e32 v10, v123, v10
	v_mul_f32_e32 v10, v10, v131
	v_cvt_pk_bf16_f32 v12, v3, v4
	v_cvt_pk_bf16_f32 v13, v5, v6
	v_cvt_pk_bf16_f32 v14, v7, v8
	v_cvt_pk_bf16_f32 v15, v9, v10
	global_store_dwordx4 v[134:135], v[12:15], off offset:2016
	ds_read_u16 v3, v114 offset:48
	ds_read_u16 v4, v114 offset:320
	ds_read_u16 v5, v114 offset:592
	ds_read_u16 v6, v114 offset:864
	ds_read_u16 v7, v114 offset:1136
	ds_read_u16 v8, v114 offset:1408
	ds_read_u16 v9, v114 offset:1680
	ds_read_u16 v10, v114 offset:1952
	s_waitcnt lgkmcnt(0)
	v_lshlrev_b32_e32 v3, 16, v3
	v_mul_f32_e32 v3, v116, v3
	v_mul_f32_e32 v3, v3, v124
	v_lshlrev_b32_e32 v4, 16, v4
	v_mul_f32_e32 v4, v117, v4
	v_mul_f32_e32 v4, v4, v125
	v_lshlrev_b32_e32 v5, 16, v5
	v_mul_f32_e32 v5, v118, v5
	v_mul_f32_e32 v5, v5, v126
	v_lshlrev_b32_e32 v6, 16, v6
	v_mul_f32_e32 v6, v119, v6
	v_mul_f32_e32 v6, v6, v127
	v_lshlrev_b32_e32 v7, 16, v7
	v_mul_f32_e32 v7, v120, v7
	v_mul_f32_e32 v7, v7, v128
	v_lshlrev_b32_e32 v8, 16, v8
	v_mul_f32_e32 v8, v121, v8
	v_mul_f32_e32 v8, v8, v129
	v_lshlrev_b32_e32 v9, 16, v9
	v_mul_f32_e32 v9, v122, v9
	v_mul_f32_e32 v9, v9, v130
	v_lshlrev_b32_e32 v10, 16, v10
	v_mul_f32_e32 v10, v123, v10
	v_mul_f32_e32 v10, v10, v131
	v_cvt_pk_bf16_f32 v12, v3, v4
	v_cvt_pk_bf16_f32 v13, v5, v6
	v_cvt_pk_bf16_f32 v14, v7, v8
	v_cvt_pk_bf16_f32 v15, v9, v10
	global_store_dwordx4 v[134:135], v[12:15], off offset:3040
	s_and_saveexec_b64 s[44:45], s[10:11]
	s_cbranch_execz .LBB0_359
	s_lshl_b64 vcc, s[40:41], 2
	v_mul_f32_e32 v0, 0x3fb8aa3b, v2
	s_add_u32 s36, s68, vcc_lo
	v_exp_f32_e32 v0, v0
	s_addc_u32 s37, s82, vcc_hi
	s_add_u32 vcc_lo, s74, s36
	s_addc_u32 vcc_hi, s75, s37
	global_store_dword v145, v0, vcc
